# attention fixed softmax reference, now guarded: original running-max loop kept as fallback when norm bound R>=48
# speedup vs baseline: 1.0146x; 1.0062x over previous
.LBB0_306:
	s_or_b64 exec, exec, s[0:1]
	v_readlane_b32 s0, v252, 1
	v_mov_b32_e32 v169, 0
	v_readlane_b32 s1, v252, 2
	v_mov_b32_e32 v5, 0x8000
	s_waitcnt lgkmcnt(0)
	s_barrier
	v_add_f32_e32 v2, v0, v2
	s_nop 0
	global_load_dword v4, v169, s[0:1] sc1
	v_add_f32_e32 v1, v1, v3
	global_load_dword v5, v5, s[62:63] offset:768 sc1
	s_mov_b32 s0, 0x3fb8aa3b
	v_lshrrev_b32_e32 v7, 4, v209
	v_lshlrev_b32_e32 v10, 4, v209
	v_mul_f32_e32 v13, 0x3fb8aa3b, v2
	v_lshrrev_b32_e32 v8, 5, v209
	v_lshrrev_b32_e32 v9, 3, v209
	v_mul_f32_e32 v14, 0x3fb8aa3b, v1
	v_and_b32_e32 v15, 51, v7
	v_and_b32_e32 v17, 0xf0, v10
	v_mul_u32_u24_e32 v7, 0x1400, v7
	v_fma_f32 v20, v2, s0, -v13
	v_rndne_f32_e32 v21, v13
	v_and_b32_e32 v8, 4, v8
	v_and_b32_e32 v16, 8, v9
	v_fma_f32 v22, v1, s0, -v14
	v_rndne_f32_e32 v23, v14
	v_or_b32_e32 v170, v17, v7
	v_fmac_f32_e32 v20, 0x32a5705f, v2
	v_sub_f32_e32 v7, v13, v21
	v_or3_b32 v8, v15, v8, v16
	v_fmac_f32_e32 v22, 0x32a5705f, v1
	v_sub_f32_e32 v14, v14, v23
	v_add_f32_e32 v7, v7, v20
	v_cvt_i32_f32_e32 v13, v21
	v_mul_u32_u24_e32 v8, 0x110, v8
	v_add_f32_e32 v14, v14, v22
	v_exp_f32_e32 v7, v7
	v_cvt_i32_f32_e32 v15, v23
	v_add3_u32 v212, 0, v8, v17
	v_exp_f32_e32 v8, v14
	s_mov_b32 s1, 0xc2ce8ed0
	v_ldexp_f32 v7, v7, v13
	v_cmp_ngt_f32_e32 vcc, s1, v2
	s_mov_b32 s33, 0x42b17218
	v_ldexp_f32 v8, v8, v15
	v_cndmask_b32_e32 v7, 0, v7, vcc
	v_cmp_ngt_f32_e32 vcc, s1, v1
	v_mov_b32_e32 v3, 0x7f800000
	s_mov_b32 s38, 0xf800000
	v_cndmask_b32_e32 v8, 0, v8, vcc
	v_cmp_nlt_f32_e32 vcc, s33, v2
	s_add_u32 s4, s62, 0xc00000
	s_addc_u32 s5, s63, 0
	v_cndmask_b32_e32 v2, v3, v7, vcc
	v_cmp_nlt_f32_e32 vcc, s33, v1
	s_add_u32 s6, s62, 0xd00000
	s_addc_u32 s7, s63, 0
	v_cndmask_b32_e32 v1, v3, v8, vcc
	v_sub_f32_e32 v1, v2, v1
	v_add_f32_e32 v172, 0x3eb60549, v1
	s_add_u32 s34, s62, 0xe00000
	s_addc_u32 s35, s63, 0
	s_add_u32 s26, s62, 0x1000000
	s_addc_u32 s27, s63, 0
	v_mov_b32_e32 v6, 0x260
	s_add_u32 s24, s62, 0x1b00000
	s_addc_u32 s25, s63, 0
	s_add_u32 s36, s62, 0x1c900000
	s_addc_u32 s37, s63, 0
	v_mul_u32_u24_e32 v11, 0x110, v167
	v_lshlrev_b32_e32 v12, 4, v166
	s_add_u32 s40, s62, 0x8000
	s_addc_u32 s41, s63, 0
	v_add3_u32 v214, 0, v11, v12
	v_lshlrev_b32_e32 v0, 3, v166
	s_add_i32 s66, s64, 0xa00
	v_lshlrev_b32_e32 v168, 2, v167
	v_and_b32_e32 v18, 0x70, v10
	v_mul_u32_u24_e32 v19, 0x10080, v9
	v_mul_u32_u24_e32 v9, 0x90, v9
	v_lshl_add_u64 v[194:195], s[30:31], 0, v[168:169]
	s_movk_i32 s30, 0xff80
	s_mov_b32 s44, 0xfffb0000
	s_movk_i32 s13, 0x1400
	v_mov_b32_e32 v171, v169
	v_lshl_add_u32 v216, v129, 2, 0
	v_lshl_add_u64 v[174:175], s[56:57], 0, v[168:169]
	s_movk_i32 s67, 0x84
	v_or_b32_e32 v219, 8, v177
	s_waitcnt vmcnt(0)
	v_mul_f32_e32 v2, v4, v5
	v_mul_f32_e32 v3, 0x4f800000, v2
	v_cmp_gt_f32_e32 vcc, s38, v2
	v_or_b32_e32 v220, 16, v177
	v_or_b32_e32 v221, 24, v177
	v_cndmask_b32_e32 v2, v2, v3, vcc
	v_sqrt_f32_e32 v3, v2
	v_lshl_add_u64 v[180:181], s[54:55], 0, v[168:169]
	v_lshl_add_u64 v[184:185], s[52:53], 0, v[168:169]
	v_lshl_add_u64 v[186:187], s[48:49], 0, v[168:169]
	v_add_u32_e32 v1, -1, v3
	v_add_u32_e32 v4, 1, v3
	v_fma_f32 v5, -v1, v3, v2
	v_fma_f32 v7, -v4, v3, v2
	v_cmp_ge_f32_e64 s[0:1], 0, v5
	v_mov_b32_e32 v5, v169
	v_lshl_add_u64 v[190:191], s[46:47], 0, v[168:169]
	v_cndmask_b32_e64 v1, v3, v1, s[0:1]
	v_cmp_lt_f32_e64 s[0:1], 0, v7
	v_mov_b32_e32 v173, v172
	v_mov_b32_e32 v165, v166
	v_cndmask_b32_e64 v1, v1, v4, s[0:1]
	v_mul_f32_e32 v3, 0x37800000, v1
	v_cndmask_b32_e32 v1, v1, v3, vcc
	v_cmp_class_f32_e32 vcc, v2, v6
	s_add_i32 s0, 0, 0x12000
	v_add_u32_e32 v217, s0, v12
	v_cndmask_b32_e32 v1, v1, v2, vcc
	v_add_f32_e32 v1, v1, v1
	v_mul_f32_e32 v1, 0x3f828f5c, v1
	v_sub_f32_e32 v253, 0, v1
	v_mov_b32_e32 v254, 0x42400000
	v_cmp_lt_f32_e64 s[98:99], v1, v254
	s_nop 1
	v_cndmask_b32_e64 v253, 0, v253, s[98:99]
	v_fmaak_f32 v213, 2.0, v1, 0x43160000
	v_lshlrev_b32_e32 v1, 7, v167
	v_sub_u32_e32 v215, v214, v1
	s_mul_i32 s0, s78, 0x2200
	v_and_b32_e32 v1, 56, v200
	s_add_i32 s0, s0, 0
	v_mul_u32_u24_e32 v3, 0x84, v1
	v_lshlrev_b32_e32 v4, 1, v1
	v_lshlrev_b32_e32 v1, 2, v177
	v_add3_u32 v218, s0, v3, v1
	v_add_u32_e32 v1, 0, v10
	v_lshlrev_b32_e32 v2, 2, v166
	s_cmpk_lt_i32 s64, 0x1480
	v_add_u32_e32 v176, s0, v168
	s_mov_b32 s0, 0x20000
	v_add_u32_e32 v224, 0xd000, v1
	v_sub_u32_e32 v1, v167, v0
	s_cselect_b64 s[42:43], -1, 0
	v_lshl_add_u64 v[178:179], s[24:25], 0, v[4:5]
	v_lshl_add_u64 v[182:183], s[26:27], 0, v[4:5]
	v_lshl_add_u64 v[188:189], s[34:35], 0, v[4:5]
	v_lshl_add_u64 v[192:193], s[6:7], 0, v[4:5]
	v_lshl_add_u64 v[196:197], s[4:5], 0, v[4:5]
	v_cmp_gt_i32_e64 s[0:1], s0, v164
	s_lshl_b32 s68, s14, 9
	v_add3_u32 v222, 0, v9, v18
	v_add_u32_e32 v223, 0xfffffe00, v209
	v_or_b32_e32 v198, v19, v18
	v_mov_b32_e32 v199, v169
	v_add_u32_e32 v225, 0xffffff80, v1
	v_lshl_add_u32 v226, s2, 12, v200
	s_lshl_b32 s69, s14, 12
	s_mov_b64 s[52:53], 0
	s_add_i32 s70, 0, 0x12400
	v_lshlrev_b32_e32 v200, 1, v0
	s_movk_i32 s71, 0x27f
	s_mov_b32 s72, 0xc2fc0000
	s_mov_b32 s73, 0xff61b1e6
	s_mov_b32 s74, 0x40c00000
	s_mov_b32 s31, -1
	s_mov_b32 s45, -1
	v_lshlrev_b32_e32 v202, 1, v2
	v_mov_b32_e32 v227, 0x358637bd
	s_movk_i32 s75, 0x2c00
	s_mov_b64 s[46:47], 0x1000
	s_mov_b32 s76, 0x6800000
	s_mov_b32 s77, 0x1a900000
	s_mov_b32 s78, 0x6801000
	s_mov_b32 s79, 0x6802000
	s_mov_b32 s80, 0x6803000
	s_mov_b32 s81, 0x6804000
	s_mov_b64 s[48:49], 0x5000
	s_mov_b32 s82, 0x1ffff
	v_mov_b32_e32 v240, v169
	v_mov_b32_e32 v241, v169
	v_mov_b32_e32 v242, v169
	v_mov_b32_e32 v243, v169
	v_mov_b32_e32 v228, 0x42800000
	v_mov_b32_e32 v229, 0x7149f2ca
	s_branch .LBB0_309

.LBB0_324:
	v_add_u32_e32 v1, 0x200, v1
	v_cmp_lt_u32_e32 vcc, s71, v1
	ds_write_b128 v0, v[240:243]
	s_or_b64 s[56:57], vcc, s[56:57]
	v_add_u32_e32 v0, 0x2000, v0
	s_andn2_b64 exec, exec, s[56:57]
	s_cbranch_execnz .LBB0_324
	s_or_b64 exec, exec, s[56:57]
	s_add_i32 s38, s54, 1
	v_cvt_f32_u32_e32 v0, s38
	v_mov_b32_e32 v63, 0
	v_mov_b32_e32 v62, v63
	v_mov_b32_e32 v61, v63
	v_mul_f32_e32 v1, -2.0, v0
	v_cmp_gt_f32_e32 vcc, s72, v1
	s_and_b64 s[56:57], vcc, exec
	s_cselect_b32 s38, 0xffffffc0, 0
	v_cndmask_b32_e32 v1, 0, v228, vcc
	v_fmac_f32_e32 v1, -2.0, v0
	v_exp_f32_e32 v0, v1
	s_sub_i32 s58, s89, 63
	v_cvt_f32_i32_e32 v2, s58
	v_mov_b32_e32 v60, v63
	v_ldexp_f32 v0, v0, s38
	v_mul_f32_e32 v201, 0x3fb8aa3b, v0
	v_div_scale_f32 v0, s[56:57], v201, v201, v213
	v_rcp_f32_e32 v1, v0
	v_div_scale_f32 v3, vcc, v213, v201, v213
	v_mov_b32_e32 v59, v63
	v_fma_f32 v4, -v0, v1, 1.0
	v_fmac_f32_e32 v1, v4, v1
	v_mul_f32_e32 v4, v3, v1
	v_fma_f32 v5, -v0, v4, v3
	v_fmac_f32_e32 v4, v5, v1
	v_fma_f32 v0, -v0, v4, v3
	v_div_fmas_f32 v0, v0, v1, v4
	v_div_fixup_f32 v0, v0, v201, v213
	v_sub_f32_e32 v0, v2, v0
	v_mul_f32_e32 v0, 0x3c800000, v0
	v_ceil_f32_e32 v1, v0
	v_cvt_i32_f32_e32 v1, v1
	v_cmp_lt_f32_e32 vcc, 0, v0
	v_mov_b32_e32 v58, v63
	v_mov_b32_e32 v57, v63
	v_readfirstlane_b32 s38, v1
	s_min_i32 s38, s38, s86
	s_and_b64 s[56:57], vcc, exec
	s_cselect_b32 s38, s38, 0
	s_sub_i32 s86, s86, s38
	s_add_i32 s38, s86, 2
	s_cmp_gt_i32 s38, -1
	v_mov_b32_e32 v56, v63
	v_mov_b32_e32 v55, v63
	v_mov_b32_e32 v54, v63
	v_mov_b32_e32 v53, v63
	v_mov_b32_e32 v52, v63
	v_mov_b32_e32 v51, v63
	v_mov_b32_e32 v50, v63
	v_mov_b32_e32 v49, v63
	v_mov_b32_e32 v48, v63
	v_mov_b32_e32 v47, v63
	v_mov_b32_e32 v46, v63
	v_mov_b32_e32 v45, v63
	v_mov_b32_e32 v44, v63
	v_mov_b32_e32 v43, v63
	v_mov_b32_e32 v42, v63
	v_mov_b32_e32 v41, v63
	v_mov_b32_e32 v40, v63
	v_mov_b32_e32 v39, v63
	v_mov_b32_e32 v38, v63
	v_mov_b32_e32 v37, v63
	v_mov_b32_e32 v36, v63
	v_mov_b32_e32 v35, v63
	v_mov_b32_e32 v34, v63
	v_mov_b32_e32 v33, v63
	v_mov_b32_e32 v32, v63
	v_mov_b32_e32 v31, v63
	v_mov_b32_e32 v30, v63
	v_mov_b32_e32 v29, v63
	v_mov_b32_e32 v28, v63
	v_mov_b32_e32 v27, v63
	v_mov_b32_e32 v26, v63
	v_mov_b32_e32 v25, v63
	v_mov_b32_e32 v24, v63
	v_mov_b32_e32 v23, v63
	v_mov_b32_e32 v22, v63
	v_mov_b32_e32 v21, v63
	v_mov_b32_e32 v20, v63
	v_mov_b32_e32 v19, v63
	v_mov_b32_e32 v18, v63
	v_mov_b32_e32 v17, v63
	v_mov_b32_e32 v16, v63
	v_mov_b32_e32 v15, v63
	v_mov_b32_e32 v14, v63
	v_mov_b32_e32 v13, v63
	v_mov_b32_e32 v12, v63
	v_mov_b32_e32 v11, v63
	v_mov_b32_e32 v10, v63
	v_mov_b32_e32 v9, v63
	v_mov_b32_e32 v8, v63
	v_mov_b32_e32 v7, v63
	v_mov_b32_e32 v6, v63
	v_mov_b32_e32 v5, v63
	v_mov_b32_e32 v4, v63
	v_mov_b32_e32 v3, v63
	v_mov_b32_e32 v2, v63
	v_mov_b32_e32 v1, v63
	v_mov_b32_e32 v0, v63
	v_mov_b32_e32 v233, v63
	s_waitcnt vmcnt(0)
	s_waitcnt lgkmcnt(0)
	s_barrier
	s_cbranch_scc0 .LBB0_347
	s_cmp_lt_u32 s84, 2
	s_cselect_b64 s[56:57], -1, 0
	s_lshl_b32 s33, s33, 1
	v_cndmask_b32_e64 v203, 0, 1, s[56:57]
	s_sub_i32 s56, 0, s33
	s_and_b32 s55, s55, 3
	s_ashr_i32 s57, s56, 31
	s_add_i32 s86, s86, 3
	s_lshl_b32 s55, s55, 14
	s_lshl_b64 s[92:93], s[56:57], 7
	s_add_u32 s33, s92, s55
	s_mul_i32 s59, s65, 0x10080
	s_addc_u32 s55, s93, 0
	s_mul_hi_u32 s58, s65, 0x10080
	s_add_u32 s92, s33, s59
	s_addc_u32 s93, s55, s58
	s_mov_b32 s55, s39
	s_mul_hi_i32 s33, s56, 0x50000
	s_mul_i32 s56, s56, 0x50000
	s_lshl_b64 s[54:55], s[54:55], 8
	s_add_u32 s54, s54, s56
	s_addc_u32 s33, s55, s33
	s_add_u32 s54, s54, s88
	v_mov_b32_e32 v80, v169
	v_mov_b32_e32 v81, v169
	s_addc_u32 s55, s33, 0
	v_mov_b32_e32 v82, v169
	v_mov_b32_e32 v83, v169
	v_mov_b32_e32 v84, v169
	v_mov_b32_e32 v85, v169
	v_mov_b32_e32 v86, v169
	v_mov_b32_e32 v87, v169
	v_mov_b32_e32 v88, v169
	v_mov_b32_e32 v89, v169
	v_mov_b32_e32 v90, v169
	v_mov_b32_e32 v91, v169
	v_mov_b32_e32 v92, v169
	v_mov_b32_e32 v93, v169
	v_mov_b32_e32 v94, v169
	v_mov_b32_e32 v95, v169
	v_mov_b32_e32 v233, 0
	v_mov_b32_e32 v64, v253
	v_mov_b32_e32 v65, v253
	v_lshl_add_u32 v230, s85, 7, v214
	s_mov_b32 s90, 0
	v_lshl_add_u64 v[204:205], s[92:93], 0, v[198:199]
	v_lshl_add_u64 v[206:207], s[54:55], 0, v[170:171]
	v_add_u32_e32 v231, s87, v225
	v_mov_b32_e32 v144, 0
	v_mov_b32_e32 v145, 0
	v_mov_b32_e32 v146, 0
	v_mov_b32_e32 v147, 0
	v_mov_b32_e32 v148, 0
	v_mov_b32_e32 v149, 0
	v_mov_b32_e32 v150, 0
	v_mov_b32_e32 v151, 0
	v_mov_b32_e32 v66, v253
	v_mov_b32_e32 v67, v253
	v_mov_b32_e32 v68, v253
	v_mov_b32_e32 v69, v253
	v_mov_b32_e32 v70, v253
	v_mov_b32_e32 v71, v253
	v_mov_b32_e32 v72, v253
	v_mov_b32_e32 v73, v253
	v_mov_b32_e32 v74, v253
	v_mov_b32_e32 v75, v253
	v_mov_b32_e32 v76, v253
	v_mov_b32_e32 v77, v253
	v_mov_b32_e32 v78, v253
	v_mov_b32_e32 v79, v253
	v_mov_b32_e32 v232, 0
	v_mov_b32_e32 v0, 0
	v_mov_b32_e32 v1, v233
	v_mov_b32_e32 v2, v233
	v_mov_b32_e32 v3, v233
	v_mov_b32_e32 v4, v233
	v_mov_b32_e32 v5, v233
	v_mov_b32_e32 v6, v233
	v_mov_b32_e32 v7, v233
	v_mov_b32_e32 v8, v233
	v_mov_b32_e32 v9, v233
	v_mov_b32_e32 v10, v233
	v_mov_b32_e32 v11, v233
	v_mov_b32_e32 v12, v233
	v_mov_b32_e32 v13, v233
	v_mov_b32_e32 v14, v233
	v_mov_b32_e32 v15, v233
	v_mov_b32_e32 v16, 0
	v_mov_b32_e32 v17, v233
	v_mov_b32_e32 v18, v233
	v_mov_b32_e32 v19, v233
	v_mov_b32_e32 v20, v233
	v_mov_b32_e32 v21, v233
	v_mov_b32_e32 v22, v233
	v_mov_b32_e32 v23, v233
	v_mov_b32_e32 v24, v233
	v_mov_b32_e32 v25, v233
	v_mov_b32_e32 v26, v233
	v_mov_b32_e32 v27, v233
	v_mov_b32_e32 v28, v233
	v_mov_b32_e32 v29, v233
	v_mov_b32_e32 v30, v233
	v_mov_b32_e32 v31, v233
	v_mov_b32_e32 v32, 0
	v_mov_b32_e32 v33, v233
	v_mov_b32_e32 v34, v233
	v_mov_b32_e32 v35, v233
	v_mov_b32_e32 v36, v233
	v_mov_b32_e32 v37, v233
	v_mov_b32_e32 v38, v233
	v_mov_b32_e32 v39, v233
	v_mov_b32_e32 v40, v233
	v_mov_b32_e32 v41, v233
	v_mov_b32_e32 v42, v233
	v_mov_b32_e32 v43, v233
	v_mov_b32_e32 v44, v233
	v_mov_b32_e32 v45, v233
	v_mov_b32_e32 v46, v233
	v_mov_b32_e32 v47, v233
	v_mov_b32_e32 v48, 0
	v_mov_b32_e32 v49, v233
	v_mov_b32_e32 v50, v233
	v_mov_b32_e32 v51, v233
	v_mov_b32_e32 v52, v233
	v_mov_b32_e32 v53, v233
	v_mov_b32_e32 v54, v233
	v_mov_b32_e32 v55, v233
	v_mov_b32_e32 v56, v233
	v_mov_b32_e32 v57, v233
	v_mov_b32_e32 v58, v233
	v_mov_b32_e32 v59, v233
	v_mov_b32_e32 v60, v233
	v_mov_b32_e32 v61, v233
	v_mov_b32_e32 v62, v233
	v_mov_b32_e32 v63, v233
	s_cmp_lg_u64 s[98:99], 0
	s_cbranch_scc1 .Lan_327

.LBB0_345:
	v_lshl_add_u64 v[204:205], v[204:205], 0, s[30:31]
	v_lshl_add_u64 v[206:207], v[206:207], 0, s[44:45]
	s_cmp_eq_u32 s86, s87
	v_add_u32_e32 v231, 64, v231
	s_waitcnt lgkmcnt(0)
	s_barrier
	s_cbranch_scc1 .LBB0_347
	s_mov_b32 s90, s87
	s_branch .LBB0_327
.Lan_327:
	s_and_b32 s88, s90, 1
	s_mul_i32 s33, s88, 0x4400
	v_add_u32_e32 v235, s33, v230
	ds_read_b128 v[156:159], v235
	ds_read_b128 v[152:155], v235 offset:32
	s_add_i32 s87, s90, 1
	s_cmp_lt_i32 s87, s38
	s_cselect_b64 s[54:55], -1, 0
	s_cmp_ge_i32 s87, s38
	s_cbranch_scc1 .Lan_329
	v_lshl_add_u64 v[96:97], s[62:63], 0, v[206:207]
	v_add_co_u32_e32 v98, vcc, 0x8f61000, v96
	s_nop 1
	v_addc_co_u32_e32 v99, vcc, 0, v97, vcc
	v_add_co_u32_e32 v96, vcc, 0x8f89000, v96
	s_nop 1
	v_addc_co_u32_e32 v97, vcc, 0, v97, vcc
	global_load_dwordx4 v[128:131], v[98:99], off
	global_load_dwordx4 v[132:135], v[96:97], off

	.amdhsa_kernel _Z14fwd_megakernel4Args
		.amdhsa_group_segment_fixed_size 0
		.amdhsa_private_segment_fixed_size 0
		.amdhsa_kernarg_size 432
		.amdhsa_user_sgpr_count 2
		.amdhsa_user_sgpr_dispatch_ptr 0
		.amdhsa_user_sgpr_queue_ptr 0
		.amdhsa_user_sgpr_kernarg_segment_ptr 1
		.amdhsa_user_sgpr_dispatch_id 0
		.amdhsa_user_sgpr_kernarg_preload_length 0
		.amdhsa_user_sgpr_kernarg_preload_offset 0
		.amdhsa_user_sgpr_private_segment_size 0
		.amdhsa_uses_dynamic_stack 0
		.amdhsa_enable_private_segment 0
		.amdhsa_system_sgpr_workgroup_id_x 1
		.amdhsa_system_sgpr_workgroup_id_y 0
		.amdhsa_system_sgpr_workgroup_id_z 0
		.amdhsa_system_sgpr_workgroup_info 0
		.amdhsa_system_vgpr_workitem_id 2
		.amdhsa_next_free_vgpr 256
		.amdhsa_next_free_sgpr 102
		.amdhsa_accum_offset 256
		.amdhsa_reserve_vcc 1
		.amdhsa_float_round_mode_32 0
		.amdhsa_float_round_mode_16_64 0
		.amdhsa_float_denorm_mode_32 3
		.amdhsa_float_denorm_mode_16_64 3
		.amdhsa_dx10_clamp 1
		.amdhsa_ieee_mode 1
		.amdhsa_fp16_overflow 0
		.amdhsa_tg_split 0
		.amdhsa_exception_fp_ieee_invalid_op 0
		.amdhsa_exception_fp_denorm_src 0
		.amdhsa_exception_fp_ieee_div_zero 0
		.amdhsa_exception_fp_ieee_overflow 0
		.amdhsa_exception_fp_ieee_underflow 0
		.amdhsa_exception_fp_ieee_inexact 0
		.amdhsa_exception_int_div_zero 0
	.end_amdhsa_kernel

amdhsa.kernels:
  - .agpr_count:     0
    .args:
      - .offset:         0
        .size:           176
        .value_kind:     by_value
      - .offset:         176
        .size:           4
        .value_kind:     hidden_block_count_x
      - .offset:         180
        .size:           4
        .value_kind:     hidden_block_count_y
      - .offset:         184
        .size:           4
        .value_kind:     hidden_block_count_z
      - .offset:         188
        .size:           2
        .value_kind:     hidden_group_size_x
      - .offset:         190
        .size:           2
        .value_kind:     hidden_group_size_y
      - .offset:         192
        .size:           2
        .value_kind:     hidden_group_size_z
      - .offset:         194
        .size:           2
        .value_kind:     hidden_remainder_x
      - .offset:         196
        .size:           2
        .value_kind:     hidden_remainder_y
      - .offset:         198
        .size:           2
        .value_kind:     hidden_remainder_z
      - .offset:         216
        .size:           8
        .value_kind:     hidden_global_offset_x
      - .offset:         224
        .size:           8
        .value_kind:     hidden_global_offset_y
      - .offset:         232
        .size:           8
        .value_kind:     hidden_global_offset_z
      - .offset:         240
        .size:           2
        .value_kind:     hidden_grid_dims
      - .offset:         264
        .size:           8
        .value_kind:     hidden_multigrid_sync_arg
      - .offset:         296
        .size:           4
        .value_kind:     hidden_dynamic_lds_size
    .group_segment_fixed_size: 0
    .kernarg_segment_align: 8
    .kernarg_segment_size: 432
    .language:       OpenCL C
    .language_version:
      - 2
      - 0
    .max_flat_workgroup_size: 512
    .name:           _Z14fwd_megakernel4Args
    .private_segment_fixed_size: 0
    .sgpr_count:     108
    .sgpr_spill_count: 12
    .symbol:         _Z14fwd_megakernel4Args.kd
    .uniform_work_group_size: 1
    .uses_dynamic_stack: false
    .vgpr_count:     256
    .vgpr_spill_count: 0
    .wavefront_size: 64
